# attention: V tile row-major in LDS + ds_read_b64_tr_b16 fragments, PV(qb1) reads hoisted above exps
# baseline (speedup 1.0000x reference)
.LBB0_450:
	s_or_b64 exec, exec, s[4:5]
	v_readlane_b32 s0, v254, 13
	v_mov_b32_e32 v1, v220
	v_readlane_b32 s1, v254, 14
	s_waitcnt lgkmcnt(0)
	s_barrier
	s_andn2_b64 vcc, exec, s[0:1]
	v_readfirstlane_b32 s3, v1
	s_cbranch_vccnz .LBB0_505
	v_ashrrev_i32_e32 v209, 3, v1
	s_movk_i32 s6, 0x90
	s_and_b64 s[4:5], s[60:61], exec
	v_and_b32_e32 v5, 7, v1
	v_mul_lo_u32 v6, v209, s6
	v_bfe_u32 v3, v1, 5, 1
	v_add_u32_e32 v6, 0, v6
	v_lshlrev_b32_e32 v7, 4, v5
	s_movk_i32 s4, 0xff72
	v_and_b32_e32 v193, 31, v1
	v_lshlrev_b32_e32 v2, 3, v3
	v_mad_u64_u32 v[8:9], s[4:5], v209, s4, v[6:7]
	v_and_or_b32 v212, v1, 63, 32
	s_cselect_b32 s0, 8, 0
	s_cselect_b32 s1, 0x200, 0
	s_ashr_i32 s26, s3, 7
	s_and_b32 s3, s3, 64
	v_lshlrev_b32_e32 v192, 3, v5
	v_lshlrev_b32_e32 v4, 2, v3
	v_mad_u32_u24 v9, v193, s6, 0
	v_lshlrev_b32_e32 v3, 4, v3
	v_mad_u32_u24 v1, v212, s6, 0
	v_add_u32_e32 v10, 0, v2
	v_mul_u32_u24_e32 v5, 0x440, v5
	v_mul_u32_u24_e32 v11, 0x88, v193
	v_mul_u32_u24_e32 v12, 0x88, v212
	v_or_b32_e32 v208, s3, v193
	v_add_u32_e32 v210, 64, v209
	v_add_u32_e32 v211, 0x80, v209
	v_add_u32_e32 v213, 0xc0, v209
	v_sub_u32_e32 v214, s3, v4
	s_xor_b32 s27, s3, 0xffffff7f
	s_lshl_b32 s30, s0, 2
	v_lshlrev_b32_e32 v194, 1, v2
	v_add_u32_e32 v215, v6, v7
	v_mul_u32_u24_e32 v216, 0xc0, v209
	v_add_u32_e32 v216, v216, v7
	v_add_u32_e32 v217, v9, v3
	v_add_u32_e32 v218, v1, v3
	v_lshlrev_b32_e32 v196, 1, v4
	v_bfe_u32 v10, v220, 2, 2
	v_bfe_u32 v11, v220, 5, 1
	v_lshl_add_u32 v10, v11, 2, v10
	v_mul_u32_u24_e32 v10, 0xc0, v10
	v_bfe_u32 v11, v220, 4, 1
	v_lshl_add_u32 v10, v11, 5, v10
	v_and_b32_e32 v11, 3, v220
	v_lshl_add_u32 v219, v11, 3, v10
	s_mov_b32 s31, s2
	s_branch .LBB0_454

.LBB0_491:
	s_waitcnt lgkmcnt(0)
	s_barrier
	ds_write_b128 v215, v[84:87]
	ds_write_b128 v216, v[80:83] offset:9216
	s_waitcnt lgkmcnt(0)
	s_barrier
	s_add_i32 s4, s14, 3
	s_cmp_ge_i32 s4, s36
	s_cbranch_scc1 .LBB0_493
	s_cmp_lt_i32 s4, s34
	s_cselect_b64 s[4:5], -1, 0
	s_and_b64 s[20:21], s[4:5], exec
	s_cselect_b32 s0, 0, s34
	s_mov_b32 s15, 0xb000000
	s_cselect_b32 s13, s3, s35
	s_cselect_b32 s46, s15, 0x100000
	s_lshl_b32 s0, s0, 6
	s_sub_i32 s0, s13, s0
	v_add_u32_e32 v4, s0, v242
	s_and_b64 s[4:5], s[4:5], exec
	s_mov_b32 s0, 0xb600000
	v_lshl_add_u64 v[2:3], v[202:203], 0, s[46:47]
	v_ashrrev_i32_e32 v5, 31, v4
	s_cselect_b32 s46, s0, 0x200000
	v_lshlrev_b64 v[4:5], 8, v[4:5]
	v_lshl_add_u64 v[6:7], v[202:203], 0, s[46:47]
	v_lshl_add_u64 v[2:3], v[2:3], 0, v[4:5]
	v_lshl_add_u64 v[4:5], v[6:7], 0, v[4:5]
	global_load_dwordx4 v[6:9], v[2:3], off
	s_nop 0
	global_load_dwordx4 v[2:5], v[4:5], off

.LBB0_498:
	v_exp_f32_e32 v14, v128
	v_exp_f32_e32 v112, v112
	v_exp_f32_e32 v15, v129
	v_exp_f32_e32 v113, v113
	v_exp_f32_e32 v204, v130
	v_exp_f32_e32 v206, v114
	v_exp_f32_e32 v205, v131
	v_exp_f32_e32 v207, v115
	v_exp_f32_e32 v10, v132
	v_exp_f32_e32 v12, v116
	v_exp_f32_e32 v11, v133
	v_exp_f32_e32 v13, v117
	v_exp_f32_e32 v128, v134
	v_exp_f32_e32 v130, v118
	v_exp_f32_e32 v129, v135
	v_exp_f32_e32 v131, v119
	v_exp_f32_e32 v118, v136
	v_exp_f32_e32 v120, v120
	v_exp_f32_e32 v119, v137
	v_exp_f32_e32 v121, v121
	v_exp_f32_e32 v132, v138
	v_exp_f32_e32 v134, v122
	v_exp_f32_e32 v133, v139
	v_exp_f32_e32 v135, v123
	v_exp_f32_e32 v114, v140
	v_exp_f32_e32 v116, v124
	v_exp_f32_e32 v115, v141
	v_exp_f32_e32 v117, v125
	v_exp_f32_e32 v122, v142
	v_exp_f32_e32 v124, v126
	v_exp_f32_e32 v123, v143
	v_exp_f32_e32 v125, v127
	ds_read_b64_tr_b16 v[136:137], v219 offset:9216
	ds_read_b64_tr_b16 v[138:139], v219 offset:10752
	v_cvt_pk_bf16_f32 v140, v14, v15
	v_cvt_pk_bf16_f32 v141, v204, v205
	v_cvt_pk_bf16_f32 v142, v10, v11
	v_cvt_pk_bf16_f32 v143, v128, v129
	v_cvt_pk_bf16_f32 v230, v118, v119
	v_cvt_pk_bf16_f32 v231, v132, v133
	v_cvt_pk_bf16_f32 v232, v114, v115
	v_cvt_pk_bf16_f32 v233, v122, v123
	s_waitcnt lgkmcnt(0)
	v_mfma_f32_32x32x16_bf16 v[64:79], v[136:139], v[140:143], v[64:79]
	ds_read_b64_tr_b16 v[136:137], v219 offset:12288
	ds_read_b64_tr_b16 v[138:139], v219 offset:13824
	v_cvt_pk_bf16_f32 v244, v112, v113
	v_cvt_pk_bf16_f32 v245, v206, v207
	v_cvt_pk_bf16_f32 v246, v12, v13
	v_cvt_pk_bf16_f32 v247, v130, v131
	v_cvt_pk_bf16_f32 v248, v120, v121
	v_cvt_pk_bf16_f32 v249, v134, v135
	v_cvt_pk_bf16_f32 v250, v116, v117
	s_waitcnt lgkmcnt(0)
	v_mfma_f32_32x32x16_bf16 v[64:79], v[136:139], v[230:233], v[64:79]
	ds_read_b64_tr_b16 v[136:137], v219 offset:15360
	ds_read_b64_tr_b16 v[138:139], v219 offset:16896
	v_cvt_pk_bf16_f32 v251, v124, v125
	s_waitcnt lgkmcnt(0)
	v_mfma_f32_32x32x16_bf16 v[64:79], v[136:139], v[244:247], v[64:79]
	ds_read_b64_tr_b16 v[136:137], v219 offset:18432
	ds_read_b64_tr_b16 v[138:139], v219 offset:19968
	s_waitcnt lgkmcnt(0)
	v_mfma_f32_32x32x16_bf16 v[64:79], v[136:139], v[248:251], v[64:79]
	ds_read_b64_tr_b16 v[136:137], v219 offset:9280
	ds_read_b64_tr_b16 v[138:139], v219 offset:10816
	s_waitcnt lgkmcnt(0)
	v_mfma_f32_32x32x16_bf16 v[48:63], v[136:139], v[140:143], v[48:63]
	ds_read_b64_tr_b16 v[136:137], v219 offset:12352
	ds_read_b64_tr_b16 v[138:139], v219 offset:13888
	s_waitcnt lgkmcnt(0)
	v_mfma_f32_32x32x16_bf16 v[48:63], v[136:139], v[230:233], v[48:63]
	ds_read_b64_tr_b16 v[136:137], v219 offset:15424
	ds_read_b64_tr_b16 v[138:139], v219 offset:16960
	s_waitcnt lgkmcnt(0)
	v_mfma_f32_32x32x16_bf16 v[48:63], v[136:139], v[244:247], v[48:63]
	ds_read_b64_tr_b16 v[136:137], v219 offset:18496
	ds_read_b64_tr_b16 v[138:139], v219 offset:20032
	s_waitcnt lgkmcnt(0)
	v_mfma_f32_32x32x16_bf16 v[48:63], v[136:139], v[248:251], v[48:63]
	s_and_b64 vcc, exec, s[4:5]
	s_cbranch_vccnz .LBB0_500
	v_add_u32_e32 v127, v212, v240
	v_add_u32_e32 v136, 0xffffff7f, v127
	v_cmp_lt_u32_e32 vcc, s91, v136
	v_add_u32_e32 v136, 0xffffff5f, v127
	s_nop 0
	v_cndmask_b32_e32 v96, v234, v96, vcc
	v_cmp_lt_u32_e32 vcc, s91, v136
	v_add_u32_e32 v136, 0xffffff7e, v127
	s_nop 0
	v_cndmask_b32_e32 v80, v234, v80, vcc
	v_cmp_lt_u32_e32 vcc, s91, v136
	v_add_u32_e32 v136, 0xffffff5e, v127
	s_nop 0
	v_cndmask_b32_e32 v97, v234, v97, vcc
	v_cmp_lt_u32_e32 vcc, s91, v136
	v_add_u32_e32 v136, 0xffffff7d, v127
	s_nop 0
	v_cndmask_b32_e32 v81, v234, v81, vcc
	v_cmp_lt_u32_e32 vcc, s91, v136
	v_add_u32_e32 v136, 0xffffff5d, v127
	s_nop 0
	v_cndmask_b32_e32 v98, v234, v98, vcc
	v_cmp_lt_u32_e32 vcc, s91, v136
	v_add_u32_e32 v136, 0xffffff7c, v127
	s_nop 0
	v_cndmask_b32_e32 v82, v234, v82, vcc
	v_cmp_lt_u32_e32 vcc, s91, v136
	v_add_u32_e32 v136, 0xffffff5c, v127
	s_nop 0
	v_cndmask_b32_e32 v99, v234, v99, vcc
	v_cmp_lt_u32_e32 vcc, s91, v136
	v_add_u32_e32 v136, 0xffffff77, v127
	s_nop 0
	v_cndmask_b32_e32 v83, v234, v83, vcc
	v_cmp_lt_u32_e32 vcc, s91, v136
	v_add_u32_e32 v136, 0xffffff57, v127
	s_nop 0
	v_cndmask_b32_e32 v100, v234, v100, vcc
	v_cmp_lt_u32_e32 vcc, s91, v136
	v_add_u32_e32 v136, 0xffffff76, v127
	s_nop 0
	v_cndmask_b32_e32 v84, v234, v84, vcc
	v_cmp_lt_u32_e32 vcc, s91, v136
	v_add_u32_e32 v136, 0xffffff56, v127
	s_nop 0
	v_cndmask_b32_e32 v101, v234, v101, vcc
	v_cmp_lt_u32_e32 vcc, s91, v136
	v_add_u32_e32 v136, 0xffffff75, v127
	s_nop 0
	v_cndmask_b32_e32 v85, v234, v85, vcc
	v_cmp_lt_u32_e32 vcc, s91, v136
	v_add_u32_e32 v136, 0xffffff55, v127
	s_nop 0
	v_cndmask_b32_e32 v102, v234, v102, vcc
	v_cmp_lt_u32_e32 vcc, s91, v136
	v_add_u32_e32 v136, 0xffffff74, v127
	s_nop 0
	v_cndmask_b32_e32 v86, v234, v86, vcc
	v_cmp_lt_u32_e32 vcc, s91, v136
	v_add_u32_e32 v136, 0xffffff54, v127
	s_nop 0
	v_cndmask_b32_e32 v103, v234, v103, vcc
	v_cmp_lt_u32_e32 vcc, s91, v136
	v_add_u32_e32 v136, 0xffffff6f, v127
	s_nop 0
	v_cndmask_b32_e32 v87, v234, v87, vcc
	v_cmp_lt_u32_e32 vcc, s91, v136
	v_add_u32_e32 v136, 0xffffff4f, v127
	s_nop 0
	v_cndmask_b32_e32 v104, v234, v104, vcc
	v_cmp_lt_u32_e32 vcc, s91, v136
	v_add_u32_e32 v136, 0xffffff6e, v127
	s_nop 0
	v_cndmask_b32_e32 v88, v234, v88, vcc
	v_cmp_lt_u32_e32 vcc, s91, v136
	v_add_u32_e32 v136, 0xffffff4e, v127
	s_nop 0
	v_cndmask_b32_e32 v105, v234, v105, vcc
	v_cmp_lt_u32_e32 vcc, s91, v136
	v_add_u32_e32 v136, 0xffffff6d, v127
	s_nop 0
	v_cndmask_b32_e32 v89, v234, v89, vcc
	v_cmp_lt_u32_e32 vcc, s91, v136
	v_add_u32_e32 v136, 0xffffff4d, v127
	s_nop 0
	v_cndmask_b32_e32 v106, v234, v106, vcc
	v_cmp_lt_u32_e32 vcc, s91, v136
	v_add_u32_e32 v136, 0xffffff6c, v127
	s_nop 0
	v_cndmask_b32_e32 v90, v234, v90, vcc
	v_cmp_lt_u32_e32 vcc, s91, v136
	v_add_u32_e32 v136, 0xffffff4c, v127
	s_nop 0
	v_cndmask_b32_e32 v107, v234, v107, vcc
	v_cmp_lt_u32_e32 vcc, s91, v136
	v_add_u32_e32 v136, 0xffffff67, v127
	s_nop 0
	v_cndmask_b32_e32 v91, v234, v91, vcc
	v_cmp_lt_u32_e32 vcc, s91, v136
	v_add_u32_e32 v136, 0xffffff47, v127
	s_nop 0
	v_cndmask_b32_e32 v108, v234, v108, vcc
	v_cmp_lt_u32_e32 vcc, s91, v136
	v_add_u32_e32 v136, 0xffffff66, v127
	s_nop 0
	v_cndmask_b32_e32 v92, v234, v92, vcc
	v_cmp_lt_u32_e32 vcc, s91, v136
	v_add_u32_e32 v136, 0xffffff46, v127
	s_nop 0
	v_cndmask_b32_e32 v109, v234, v109, vcc
	v_cmp_lt_u32_e32 vcc, s91, v136
	v_add_u32_e32 v136, 0xffffff65, v127
	s_nop 0
	v_cndmask_b32_e32 v93, v234, v93, vcc
	v_cmp_lt_u32_e32 vcc, s91, v136
	v_add_u32_e32 v136, 0xffffff45, v127
	s_nop 0
	v_cndmask_b32_e32 v110, v234, v110, vcc
	v_cmp_lt_u32_e32 vcc, s91, v136
	v_add_u32_e32 v136, 0xffffff64, v127
	v_add_u32_e32 v127, 0xffffff44, v127
	v_cndmask_b32_e32 v94, v234, v94, vcc
	v_cmp_lt_u32_e32 vcc, s91, v136
	s_nop 1
	v_cndmask_b32_e32 v111, v234, v111, vcc
	v_cmp_lt_u32_e32 vcc, s91, v127
	s_nop 1
	v_cndmask_b32_e32 v95, v234, v95, vcc

.LBB0_502:
	v_pk_add_f32 v[132:133], v[134:135], v[132:133]
	v_pk_add_f32 v[134:135], v[206:207], v[204:205]
	v_pk_add_f32 v[122:123], v[124:125], v[122:123]
	v_pk_add_f32 v[124:125], v[130:131], v[128:129]
	v_pk_add_f32 v[118:119], v[120:121], v[118:119]
	v_pk_add_f32 v[14:15], v[112:113], v[14:15]
	v_pk_add_f32 v[112:113], v[116:117], v[114:115]
	v_pk_add_f32 v[10:11], v[12:13], v[10:11]
	v_pk_add_f32 v[12:13], v[14:15], v[118:119]
	v_pk_add_f32 v[10:11], v[10:11], v[112:113]
	v_pk_add_f32 v[14:15], v[124:125], v[122:123]
	v_pk_add_f32 v[112:113], v[134:135], v[132:133]
	v_pk_add_f32 v[10:11], v[12:13], v[10:11]
	v_pk_add_f32 v[14:15], v[112:113], v[14:15]
	v_add_f32_e32 v10, v10, v11
	v_add_f32_e32 v11, v14, v15
	v_add_f32_e32 v10, v10, v11
	v_add_f32_e32 v241, v241, v10
	ds_read_b64_tr_b16 v[128:129], v219 offset:9216
	ds_read_b64_tr_b16 v[130:131], v219 offset:10752
	ds_read_b64_tr_b16 v[132:133], v219 offset:12288
	ds_read_b64_tr_b16 v[134:135], v219 offset:13824
	ds_read_b64_tr_b16 v[136:137], v219 offset:15360
	ds_read_b64_tr_b16 v[138:139], v219 offset:16896
	ds_read_b64_tr_b16 v[140:141], v219 offset:18432
	ds_read_b64_tr_b16 v[142:143], v219 offset:19968
	v_exp_f32_e32 v10, v96
	v_exp_f32_e32 v14, v80
	v_exp_f32_e32 v11, v97
	v_exp_f32_e32 v15, v81
	v_exp_f32_e32 v12, v98
	v_exp_f32_e32 v82, v82
	v_exp_f32_e32 v13, v99
	v_exp_f32_e32 v83, v83
	v_exp_f32_e32 v80, v100
	v_exp_f32_e32 v84, v84
	v_exp_f32_e32 v81, v101
	v_exp_f32_e32 v85, v85
	v_exp_f32_e32 v96, v102
	v_exp_f32_e32 v86, v86
	v_exp_f32_e32 v97, v103
	v_exp_f32_e32 v87, v87
	s_waitcnt lgkmcnt(7)
	ds_read_b64_tr_b16 v[122:123], v219 offset:9280
	ds_read_b64_tr_b16 v[124:125], v219 offset:10816
	ds_read_b64_tr_b16 v[204:205], v219 offset:12352
	ds_read_b64_tr_b16 v[206:207], v219 offset:13888
	ds_read_b64_tr_b16 v[230:231], v219 offset:15424
	ds_read_b64_tr_b16 v[232:233], v219 offset:16960
	ds_read_b64_tr_b16 v[244:245], v219 offset:18496
	ds_read_b64_tr_b16 v[246:247], v219 offset:20032
	v_exp_f32_e32 v98, v104
	v_exp_f32_e32 v88, v88
	v_exp_f32_e32 v99, v105
	v_exp_f32_e32 v89, v89
	v_exp_f32_e32 v100, v106
	v_exp_f32_e32 v90, v90
	v_exp_f32_e32 v101, v107
	v_exp_f32_e32 v91, v91
	v_exp_f32_e32 v102, v108
	v_exp_f32_e32 v92, v92
	v_exp_f32_e32 v103, v109
	v_exp_f32_e32 v104, v110
	v_exp_f32_e32 v94, v94
	v_exp_f32_e32 v105, v111
	v_exp_f32_e32 v95, v95
	v_exp_f32_e32 v93, v93
	v_pk_add_f32 v[106:107], v[90:91], v[100:101]
	v_pk_add_f32 v[108:109], v[82:83], v[12:13]
	v_pk_add_f32 v[110:111], v[94:95], v[104:105]
	v_pk_add_f32 v[112:113], v[86:87], v[96:97]
	v_pk_add_f32 v[114:115], v[88:89], v[98:99]
	v_pk_add_f32 v[116:117], v[14:15], v[10:11]
	v_pk_add_f32 v[118:119], v[92:93], v[102:103]
	v_pk_add_f32 v[120:121], v[84:85], v[80:81]
	v_pk_add_f32 v[114:115], v[116:117], v[114:115]
	v_pk_add_f32 v[118:119], v[120:121], v[118:119]
	v_pk_add_f32 v[110:111], v[112:113], v[110:111]
	v_pk_add_f32 v[106:107], v[108:109], v[106:107]
	v_pk_add_f32 v[108:109], v[114:115], v[118:119]
	v_pk_add_f32 v[106:107], v[106:107], v[110:111]
	s_nop 0
	v_pk_mov_b32 v[110:111], v[108:109], v[106:107] op_sel:[1,0]
	v_mov_b32_e32 v109, v107
	v_pk_add_f32 v[106:107], v[110:111], v[108:109]
	s_nop 0
	v_add_f32_e32 v106, v106, v107
	v_cvt_pk_bf16_f32 v10, v10, v11
	v_cvt_pk_bf16_f32 v11, v12, v13
	v_cvt_pk_bf16_f32 v12, v80, v81
	v_cvt_pk_bf16_f32 v13, v96, v97
	v_cvt_pk_bf16_f32 v81, v82, v83
	v_cvt_pk_bf16_f32 v82, v84, v85
	v_cvt_pk_bf16_f32 v84, v98, v99
	v_cvt_pk_bf16_f32 v88, v88, v89
	v_cvt_pk_bf16_f32 v89, v90, v91
	v_cvt_pk_bf16_f32 v90, v92, v93
	v_cvt_pk_bf16_f32 v91, v94, v95
	v_cvt_pk_bf16_f32 v83, v86, v87
	v_cvt_pk_bf16_f32 v85, v100, v101
	v_cvt_pk_bf16_f32 v86, v102, v103
	v_cvt_pk_bf16_f32 v87, v104, v105
	v_cvt_pk_bf16_f32 v80, v14, v15
	v_add_f32_e32 v238, v238, v106
	s_waitcnt lgkmcnt(0)
	v_mfma_f32_32x32x16_bf16 v[32:47], v[128:131], v[10:13], v[32:47]
	v_mfma_f32_32x32x16_bf16 v[32:47], v[132:135], v[84:87], v[32:47]
	v_mfma_f32_32x32x16_bf16 v[32:47], v[136:139], v[80:83], v[32:47]
	v_mfma_f32_32x32x16_bf16 v[32:47], v[140:143], v[88:91], v[32:47]
	v_mfma_f32_32x32x16_bf16 v[16:31], v[122:125], v[10:13], v[16:31]
	v_mfma_f32_32x32x16_bf16 v[16:31], v[204:207], v[84:87], v[16:31]
	v_mfma_f32_32x32x16_bf16 v[16:31], v[230:233], v[80:83], v[16:31]
	v_mfma_f32_32x32x16_bf16 v[16:31], v[244:247], v[88:91], v[16:31]
